# v6 plus write-through sc1 stores in the GEMM1 epilogue (U and gate tiles) to shrink the grid-barrier L2 write-back
# speedup vs baseline: 1.0100x; 1.0093x over previous
; __device__ __forceinline__ unsigned cvt_pk_bf16(float lo, float hi) { unsigned r; asm volatile("v_cvt_pk_bf16_f32 %0, %1, %2" : "=v"(r) : "v"(lo), "v"(hi)); return r; }
; __device__ __forceinline__ float fast_sigmoid(float x) { return __builtin_amdgcn_rcpf(1.0f + __builtin_amdgcn_exp2f(-1.4426950408889634f * x)); }
;     __device__ __forceinline__ void operator()(const f32x4 (&acc)[2][2][4][2], const Unit& u, int wr, int wc, int fr, int fq) const {
;     ...
; #pragma unroll
;         for (int ai = 0; ai < 2; ++ai)
; #pragma unroll
;             for (int m = 0; m < 4; ++m) { bf16_t* rowp = base + (size_t)(row0 + ai * HALF + m * 16) * ldc + col0;
;                 const float rs = rsq[ai][m];
; #pragma unroll
;                 for (int bj = 0; bj < 2; ++bj) { f32x4 v0 = acc[ai][bj][m][0] * rs + bv[bj][0], v1 = acc[ai][bj][m][1] * rs + bv[bj][1];
;                     if (isg) {
; #pragma unroll
;                         for (int e = 0; e < 4; ++e) { v0[e] = fast_sigmoid(v0[e]); v1[e] = fast_sigmoid(v1[e]); } }
;                     u32x4 w; w.x = cvt_pk_bf16(v0[0], v0[1]); w.y = cvt_pk_bf16(v0[2], v0[3]); w.z = cvt_pk_bf16(v1[0], v1[1]); w.w = cvt_pk_bf16(v1[2], v1[3]);
;                     *(u32x4*)(rowp + bj * HALF) = w; } }
.LBB0_258:
	s_and_b64 s[12:13], s[52:53], exec
	v_readlane_b32 s12, v252, 39
	s_cselect_b32 s12, s78, s12
	v_readlane_b32 s13, v252, 38
	s_cselect_b32 s13, s35, s13
	v_mov_b32_e32 v123, s12
	s_movk_i32 s12, 0x1500
	v_mov_b32_e32 v122, s13
	s_cselect_b32 s12, 0xc00, s12
	v_lshl_add_u64 v[122:123], v[164:165], 1, v[122:123]
	v_mad_i64_i32 v[124:125], s[24:25], s12, v146, 0
	v_lshl_add_u64 v[124:125], v[124:125], 1, v[122:123]
	v_cvt_pk_bf16_f32 v126, v126, v127
	v_cvt_pk_bf16_f32 v127, v128, v129
	v_mov_b32_e32 v167, v166
	v_cvt_pk_bf16_f32 v128, v170, v171
	v_cvt_pk_bf16_f32 v129, v168, v169
	flat_store_dwordx4 v[124:125], v[126:129] sc1
	s_waitcnt lgkmcnt(0)
	v_pk_fma_f32 v[118:119], v[118:119], v[166:167], v[134:135]
	s_and_b64 vcc, exec, s[44:45]
	v_mov_b32_e32 v126, v166
	v_mov_b32_e32 v127, v166
	v_pk_fma_f32 v[120:121], v[120:121], v[126:127], v[136:137]
	v_pk_fma_f32 v[116:117], v[116:117], v[126:127], v[132:133]
	v_pk_fma_f32 v[114:115], v[114:115], v[166:167], v[130:131]
	s_cbranch_vccnz .LBB0_260
	v_mul_f32_e32 v0, 0xbfb8aa3b, v118
	v_exp_f32_e32 v0, v0
	v_mul_f32_e32 v115, 0xbfb8aa3b, v115
	v_exp_f32_e32 v115, v115
	v_mul_f32_e32 v114, 0xbfb8aa3b, v114
	v_add_f32_e32 v0, 1.0, v0
	v_rcp_f32_e32 v118, v0
	v_mul_f32_e32 v0, 0xbfb8aa3b, v119
	v_exp_f32_e32 v0, v0
	v_exp_f32_e32 v114, v114
	v_add_f32_e32 v0, 1.0, v0
	v_rcp_f32_e32 v119, v0
	v_add_f32_e32 v0, 1.0, v115
	v_mul_f32_e32 v115, 0xbfb8aa3b, v120
	v_exp_f32_e32 v120, v115
	v_mul_f32_e32 v115, 0xbfb8aa3b, v116
	v_exp_f32_e32 v116, v115
	v_rcp_f32_e32 v115, v0
	v_add_f32_e32 v0, 1.0, v120
	v_rcp_f32_e32 v120, v0
	v_add_f32_e32 v0, 1.0, v116
	v_mul_f32_e32 v116, 0xbfb8aa3b, v121
	v_exp_f32_e32 v121, v116
	v_mul_f32_e32 v116, 0xbfb8aa3b, v117
	v_exp_f32_e32 v117, v116
	v_rcp_f32_e32 v116, v0
	v_add_f32_e32 v0, 1.0, v121
	v_add_f32_e32 v114, 1.0, v114
	v_rcp_f32_e32 v121, v0
	v_add_f32_e32 v0, 1.0, v117
	v_rcp_f32_e32 v114, v114
	v_rcp_f32_e32 v117, v0
.LBB0_260:
	v_cvt_pk_bf16_f32 v118, v118, v119
	v_cvt_pk_bf16_f32 v119, v120, v121
	v_cvt_pk_bf16_f32 v120, v114, v115
	v_pk_fma_f32 v[112:113], v[112:113], v[162:163], v[144:145] op_sel_hi:[1,0,1]
	v_pk_fma_f32 v[110:111], v[110:111], v[162:163], v[142:143] op_sel_hi:[1,0,1]
	v_pk_fma_f32 v[108:109], v[108:109], v[162:163], v[140:141] op_sel_hi:[1,0,1]
	s_and_b64 vcc, exec, s[44:45]
	v_pk_fma_f32 v[114:115], v[106:107], v[162:163], v[138:139] op_sel_hi:[1,0,1]
	v_cvt_pk_bf16_f32 v121, v116, v117
	flat_store_dwordx4 v[124:125], v[118:121] offset:256 sc1
	s_cbranch_vccnz .LBB0_262
	v_mul_f32_e32 v0, 0xbfb8aa3b, v110
	v_exp_f32_e32 v0, v0
	v_mul_f32_e32 v106, 0xbfb8aa3b, v114
	v_exp_f32_e32 v106, v106
	v_mul_f32_e32 v107, 0xbfb8aa3b, v115
	v_add_f32_e32 v0, 1.0, v0
	v_rcp_f32_e32 v110, v0
	v_mul_f32_e32 v0, 0xbfb8aa3b, v111
	v_exp_f32_e32 v0, v0
	v_exp_f32_e32 v107, v107
	v_add_f32_e32 v106, 1.0, v106
	v_rcp_f32_e32 v114, v106
	v_add_f32_e32 v0, 1.0, v0
	v_mul_f32_e32 v106, 0xbfb8aa3b, v112
	v_rcp_f32_e32 v111, v0
	v_add_f32_e32 v0, 1.0, v107
	v_exp_f32_e32 v106, v106
	v_mul_f32_e32 v107, 0xbfb8aa3b, v108
	v_exp_f32_e32 v107, v107
	v_rcp_f32_e32 v115, v0
	v_add_f32_e32 v0, 1.0, v106
	v_mul_f32_e32 v106, 0xbfb8aa3b, v113
	v_rcp_f32_e32 v112, v0
	v_add_f32_e32 v0, 1.0, v107
	v_exp_f32_e32 v106, v106
	v_mul_f32_e32 v107, 0xbfb8aa3b, v109
	v_exp_f32_e32 v107, v107
	v_rcp_f32_e32 v108, v0
	v_add_f32_e32 v0, 1.0, v106
	v_rcp_f32_e32 v113, v0
	v_add_f32_e32 v0, 1.0, v107
	v_rcp_f32_e32 v109, v0
.LBB0_262:
	v_or_b32_e32 v0, 16, v146
	v_mov_b32_e32 v163, v162
	v_mad_i64_i32 v[106:107], s[24:25], s12, v0, 0
	v_cvt_pk_bf16_f32 v110, v110, v111
	v_cvt_pk_bf16_f32 v111, v112, v113
	v_cvt_pk_bf16_f32 v112, v114, v115
	v_cvt_pk_bf16_f32 v113, v108, v109
	v_mov_b32_e32 v108, v162
	v_mov_b32_e32 v109, v162
	v_lshl_add_u64 v[106:107], v[106:107], 1, v[122:123]
	v_pk_fma_f32 v[104:105], v[104:105], v[108:109], v[136:137]
	v_pk_fma_f32 v[102:103], v[102:103], v[162:163], v[134:135]
	v_pk_fma_f32 v[100:101], v[100:101], v[108:109], v[132:133]
	s_and_b64 vcc, exec, s[44:45]
	v_pk_fma_f32 v[98:99], v[98:99], v[162:163], v[130:131]
	flat_store_dwordx4 v[106:107], v[110:113] sc1
	s_cbranch_vccnz .LBB0_264
	v_mul_f32_e32 v0, 0xbfb8aa3b, v102
	v_exp_f32_e32 v0, v0
	v_mul_f32_e32 v99, 0xbfb8aa3b, v99
	v_exp_f32_e32 v99, v99
	v_mul_f32_e32 v98, 0xbfb8aa3b, v98
	v_add_f32_e32 v0, 1.0, v0
	v_rcp_f32_e32 v102, v0
	v_mul_f32_e32 v0, 0xbfb8aa3b, v103
	v_exp_f32_e32 v0, v0
	v_exp_f32_e32 v98, v98
	v_add_f32_e32 v0, 1.0, v0
	v_rcp_f32_e32 v103, v0
	v_add_f32_e32 v0, 1.0, v99
	v_mul_f32_e32 v99, 0xbfb8aa3b, v104
	v_exp_f32_e32 v104, v99
	v_mul_f32_e32 v99, 0xbfb8aa3b, v100
	v_exp_f32_e32 v100, v99
	v_rcp_f32_e32 v99, v0
	v_add_f32_e32 v0, 1.0, v104
	v_rcp_f32_e32 v104, v0
	v_add_f32_e32 v0, 1.0, v100
	v_mul_f32_e32 v100, 0xbfb8aa3b, v105
	v_exp_f32_e32 v105, v100
	v_mul_f32_e32 v100, 0xbfb8aa3b, v101
	v_exp_f32_e32 v101, v100
	v_rcp_f32_e32 v100, v0
	v_add_f32_e32 v0, 1.0, v105
	v_add_f32_e32 v98, 1.0, v98
	v_rcp_f32_e32 v105, v0
	v_add_f32_e32 v0, 1.0, v101
	v_rcp_f32_e32 v98, v98
	v_rcp_f32_e32 v101, v0
; __device__ __forceinline__ unsigned cvt_pk_bf16(float lo, float hi) { unsigned r; asm volatile("v_cvt_pk_bf16_f32 %0, %1, %2" : "=v"(r) : "v"(lo), "v"(hi)); return r; }
; __device__ __forceinline__ float fast_sigmoid(float x) { return __builtin_amdgcn_rcpf(1.0f + __builtin_amdgcn_exp2f(-1.4426950408889634f * x)); }
;     __device__ __forceinline__ void operator()(const f32x4 (&acc)[2][2][4][2], const Unit& u, int wr, int wc, int fr, int fq) const {
;     ...
; #pragma unroll
;         for (int ai = 0; ai < 2; ++ai)
; #pragma unroll
;             for (int m = 0; m < 4; ++m) { bf16_t* rowp = base + (size_t)(row0 + ai * HALF + m * 16) * ldc + col0;
;                 const float rs = rsq[ai][m];
; #pragma unroll
;                 for (int bj = 0; bj < 2; ++bj) { f32x4 v0 = acc[ai][bj][m][0] * rs + bv[bj][0], v1 = acc[ai][bj][m][1] * rs + bv[bj][1];
;                     if (isg) {
; #pragma unroll
;                         for (int e = 0; e < 4; ++e) { v0[e] = fast_sigmoid(v0[e]); v1[e] = fast_sigmoid(v1[e]); } }
;                     u32x4 w; w.x = cvt_pk_bf16(v0[0], v0[1]); w.y = cvt_pk_bf16(v0[2], v0[3]); w.z = cvt_pk_bf16(v1[0], v1[1]); w.w = cvt_pk_bf16(v1[2], v1[3]);
;                     *(u32x4*)(rowp + bj * HALF) = w; } }
.LBB0_264:
	v_cvt_pk_bf16_f32 v102, v102, v103
	v_cvt_pk_bf16_f32 v103, v104, v105
	v_cvt_pk_bf16_f32 v104, v98, v99
	v_pk_fma_f32 v[96:97], v[96:97], v[160:161], v[144:145] op_sel_hi:[1,0,1]
	v_pk_fma_f32 v[94:95], v[94:95], v[160:161], v[142:143] op_sel_hi:[1,0,1]
	v_pk_fma_f32 v[92:93], v[92:93], v[160:161], v[140:141] op_sel_hi:[1,0,1]
	s_and_b64 vcc, exec, s[44:45]
	v_pk_fma_f32 v[98:99], v[90:91], v[160:161], v[138:139] op_sel_hi:[1,0,1]
	v_cvt_pk_bf16_f32 v105, v100, v101
	flat_store_dwordx4 v[106:107], v[102:105] offset:256 sc1
	s_cbranch_vccnz .LBB0_266
	v_mul_f32_e32 v0, 0xbfb8aa3b, v94
	v_exp_f32_e32 v0, v0
	v_mul_f32_e32 v90, 0xbfb8aa3b, v98
	v_exp_f32_e32 v90, v90
	v_mul_f32_e32 v91, 0xbfb8aa3b, v99
	v_add_f32_e32 v0, 1.0, v0
	v_rcp_f32_e32 v94, v0
	v_mul_f32_e32 v0, 0xbfb8aa3b, v95
	v_exp_f32_e32 v0, v0
	v_exp_f32_e32 v91, v91
	v_add_f32_e32 v90, 1.0, v90
	v_rcp_f32_e32 v98, v90
	v_add_f32_e32 v0, 1.0, v0
	v_mul_f32_e32 v90, 0xbfb8aa3b, v96
	v_rcp_f32_e32 v95, v0
	v_add_f32_e32 v0, 1.0, v91
	v_exp_f32_e32 v90, v90
	v_mul_f32_e32 v91, 0xbfb8aa3b, v92
	v_exp_f32_e32 v91, v91
	v_rcp_f32_e32 v99, v0
	v_add_f32_e32 v0, 1.0, v90
	v_mul_f32_e32 v90, 0xbfb8aa3b, v97
	v_rcp_f32_e32 v96, v0
	v_add_f32_e32 v0, 1.0, v91
	v_exp_f32_e32 v90, v90
	v_mul_f32_e32 v91, 0xbfb8aa3b, v93
	v_exp_f32_e32 v91, v91
	v_rcp_f32_e32 v92, v0
	v_add_f32_e32 v0, 1.0, v90
	v_rcp_f32_e32 v97, v0
	v_add_f32_e32 v0, 1.0, v91
	v_rcp_f32_e32 v93, v0
.LBB0_266:
	v_or_b32_e32 v0, 32, v146
	v_mov_b32_e32 v161, v160
	v_mad_i64_i32 v[90:91], s[24:25], s12, v0, 0
	v_cvt_pk_bf16_f32 v94, v94, v95
	v_cvt_pk_bf16_f32 v95, v96, v97
	v_cvt_pk_bf16_f32 v96, v98, v99
	v_cvt_pk_bf16_f32 v97, v92, v93
	v_mov_b32_e32 v92, v160
	v_mov_b32_e32 v93, v160
	v_lshl_add_u64 v[90:91], v[90:91], 1, v[122:123]
	v_pk_fma_f32 v[88:89], v[88:89], v[92:93], v[136:137]
	v_pk_fma_f32 v[86:87], v[86:87], v[160:161], v[134:135]
	v_pk_fma_f32 v[84:85], v[84:85], v[92:93], v[132:133]
	s_and_b64 vcc, exec, s[44:45]
	v_pk_fma_f32 v[82:83], v[82:83], v[160:161], v[130:131]
	flat_store_dwordx4 v[90:91], v[94:97] sc1
	s_cbranch_vccnz .LBB0_268
	v_mul_f32_e32 v0, 0xbfb8aa3b, v86
	v_exp_f32_e32 v0, v0
	v_mul_f32_e32 v83, 0xbfb8aa3b, v83
	v_exp_f32_e32 v83, v83
	v_mul_f32_e32 v82, 0xbfb8aa3b, v82
	v_add_f32_e32 v0, 1.0, v0
	v_rcp_f32_e32 v86, v0
	v_mul_f32_e32 v0, 0xbfb8aa3b, v87
	v_exp_f32_e32 v0, v0
	v_exp_f32_e32 v82, v82
	v_add_f32_e32 v0, 1.0, v0
	v_rcp_f32_e32 v87, v0
	v_add_f32_e32 v0, 1.0, v83
	v_mul_f32_e32 v83, 0xbfb8aa3b, v88
	v_exp_f32_e32 v88, v83
	v_mul_f32_e32 v83, 0xbfb8aa3b, v84
	v_exp_f32_e32 v84, v83
	v_rcp_f32_e32 v83, v0
	v_add_f32_e32 v0, 1.0, v88
	v_rcp_f32_e32 v88, v0
	v_add_f32_e32 v0, 1.0, v84
	v_mul_f32_e32 v84, 0xbfb8aa3b, v89
	v_exp_f32_e32 v89, v84
	v_mul_f32_e32 v84, 0xbfb8aa3b, v85
	v_exp_f32_e32 v85, v84
	v_rcp_f32_e32 v84, v0
	v_add_f32_e32 v0, 1.0, v89
	v_add_f32_e32 v82, 1.0, v82
	v_rcp_f32_e32 v89, v0
	v_add_f32_e32 v0, 1.0, v85
	v_rcp_f32_e32 v82, v82
	v_rcp_f32_e32 v85, v0
.LBB0_268:
	v_cvt_pk_bf16_f32 v86, v86, v87
	v_cvt_pk_bf16_f32 v87, v88, v89
	v_cvt_pk_bf16_f32 v88, v82, v83
	v_pk_fma_f32 v[80:81], v[80:81], v[158:159], v[144:145] op_sel_hi:[1,0,1]
	v_pk_fma_f32 v[78:79], v[78:79], v[158:159], v[142:143] op_sel_hi:[1,0,1]
	v_pk_fma_f32 v[76:77], v[76:77], v[158:159], v[140:141] op_sel_hi:[1,0,1]
	s_and_b64 vcc, exec, s[44:45]
	v_pk_fma_f32 v[82:83], v[74:75], v[158:159], v[138:139] op_sel_hi:[1,0,1]
	v_cvt_pk_bf16_f32 v89, v84, v85
	flat_store_dwordx4 v[90:91], v[86:89] offset:256 sc1
	s_cbranch_vccnz .LBB0_270
	v_mul_f32_e32 v0, 0xbfb8aa3b, v78
	v_exp_f32_e32 v0, v0
	v_mul_f32_e32 v74, 0xbfb8aa3b, v82
	v_exp_f32_e32 v74, v74
	v_mul_f32_e32 v75, 0xbfb8aa3b, v83
	v_add_f32_e32 v0, 1.0, v0
	v_rcp_f32_e32 v78, v0
	v_mul_f32_e32 v0, 0xbfb8aa3b, v79
	v_exp_f32_e32 v0, v0
	v_exp_f32_e32 v75, v75
	v_add_f32_e32 v74, 1.0, v74
	v_rcp_f32_e32 v82, v74
	v_add_f32_e32 v0, 1.0, v0
	v_mul_f32_e32 v74, 0xbfb8aa3b, v80
	v_rcp_f32_e32 v79, v0
	v_add_f32_e32 v0, 1.0, v75
	v_exp_f32_e32 v74, v74
	v_mul_f32_e32 v75, 0xbfb8aa3b, v76
	v_exp_f32_e32 v75, v75
	v_rcp_f32_e32 v83, v0
	v_add_f32_e32 v0, 1.0, v74
	v_mul_f32_e32 v74, 0xbfb8aa3b, v81
	v_rcp_f32_e32 v80, v0
	v_add_f32_e32 v0, 1.0, v75
	v_exp_f32_e32 v74, v74
	v_mul_f32_e32 v75, 0xbfb8aa3b, v77
	v_exp_f32_e32 v75, v75
	v_rcp_f32_e32 v76, v0
	v_add_f32_e32 v0, 1.0, v74
	v_rcp_f32_e32 v81, v0
	v_add_f32_e32 v0, 1.0, v75
	v_rcp_f32_e32 v77, v0
.LBB0_270:
	v_or_b32_e32 v0, 48, v146
	v_mov_b32_e32 v159, v158
	v_mad_i64_i32 v[74:75], s[24:25], s12, v0, 0
	v_cvt_pk_bf16_f32 v78, v78, v79
	v_cvt_pk_bf16_f32 v79, v80, v81
	v_cvt_pk_bf16_f32 v80, v82, v83
	v_cvt_pk_bf16_f32 v81, v76, v77
	v_mov_b32_e32 v76, v158
	v_mov_b32_e32 v77, v158
	v_lshl_add_u64 v[74:75], v[74:75], 1, v[122:123]
	v_pk_fma_f32 v[72:73], v[72:73], v[76:77], v[136:137]
	v_pk_fma_f32 v[70:71], v[70:71], v[158:159], v[134:135]
	v_pk_fma_f32 v[68:69], v[68:69], v[76:77], v[132:133]
	s_and_b64 vcc, exec, s[44:45]
	v_pk_fma_f32 v[66:67], v[66:67], v[158:159], v[130:131]
	flat_store_dwordx4 v[74:75], v[78:81] sc1
	s_cbranch_vccnz .LBB0_272
	v_mul_f32_e32 v0, 0xbfb8aa3b, v70
	v_exp_f32_e32 v0, v0
	v_mul_f32_e32 v67, 0xbfb8aa3b, v67
	v_exp_f32_e32 v67, v67
	v_mul_f32_e32 v66, 0xbfb8aa3b, v66
	v_add_f32_e32 v0, 1.0, v0
	v_rcp_f32_e32 v70, v0
	v_mul_f32_e32 v0, 0xbfb8aa3b, v71
	v_exp_f32_e32 v0, v0
	v_exp_f32_e32 v66, v66
	v_add_f32_e32 v0, 1.0, v0
	v_rcp_f32_e32 v71, v0
	v_add_f32_e32 v0, 1.0, v67
	v_mul_f32_e32 v67, 0xbfb8aa3b, v72
	v_exp_f32_e32 v72, v67
	v_mul_f32_e32 v67, 0xbfb8aa3b, v68
	v_exp_f32_e32 v68, v67
	v_rcp_f32_e32 v67, v0
	v_add_f32_e32 v0, 1.0, v72
	v_rcp_f32_e32 v72, v0
	v_add_f32_e32 v0, 1.0, v68
	v_mul_f32_e32 v68, 0xbfb8aa3b, v73
	v_exp_f32_e32 v73, v68
	v_mul_f32_e32 v68, 0xbfb8aa3b, v69
	v_exp_f32_e32 v69, v68
	v_rcp_f32_e32 v68, v0
	v_add_f32_e32 v0, 1.0, v73
	v_add_f32_e32 v66, 1.0, v66
	v_rcp_f32_e32 v73, v0
	v_add_f32_e32 v0, 1.0, v69
	v_rcp_f32_e32 v66, v66
	v_rcp_f32_e32 v69, v0
; __device__ __forceinline__ unsigned cvt_pk_bf16(float lo, float hi) { unsigned r; asm volatile("v_cvt_pk_bf16_f32 %0, %1, %2" : "=v"(r) : "v"(lo), "v"(hi)); return r; }
; __device__ __forceinline__ float fast_sigmoid(float x) { return __builtin_amdgcn_rcpf(1.0f + __builtin_amdgcn_exp2f(-1.4426950408889634f * x)); }
;     __device__ __forceinline__ void operator()(const f32x4 (&acc)[2][2][4][2], const Unit& u, int wr, int wc, int fr, int fq) const {
;     ...
; #pragma unroll
;         for (int ai = 0; ai < 2; ++ai)
; #pragma unroll
;             for (int m = 0; m < 4; ++m) { bf16_t* rowp = base + (size_t)(row0 + ai * HALF + m * 16) * ldc + col0;
;                 const float rs = rsq[ai][m];
; #pragma unroll
;                 for (int bj = 0; bj < 2; ++bj) { f32x4 v0 = acc[ai][bj][m][0] * rs + bv[bj][0], v1 = acc[ai][bj][m][1] * rs + bv[bj][1];
;                     if (isg) {
; #pragma unroll
;                         for (int e = 0; e < 4; ++e) { v0[e] = fast_sigmoid(v0[e]); v1[e] = fast_sigmoid(v1[e]); } }
;                     u32x4 w; w.x = cvt_pk_bf16(v0[0], v0[1]); w.y = cvt_pk_bf16(v0[2], v0[3]); w.z = cvt_pk_bf16(v1[0], v1[1]); w.w = cvt_pk_bf16(v1[2], v1[3]);
;                     *(u32x4*)(rowp + bj * HALF) = w; } }
.LBB0_272:
	v_cvt_pk_bf16_f32 v70, v70, v71
	v_cvt_pk_bf16_f32 v71, v72, v73
	v_cvt_pk_bf16_f32 v72, v66, v67
	v_pk_fma_f32 v[64:65], v[64:65], v[154:155], v[144:145] op_sel_hi:[1,0,1]
	v_pk_fma_f32 v[62:63], v[62:63], v[154:155], v[142:143] op_sel_hi:[1,0,1]
	v_pk_fma_f32 v[60:61], v[60:61], v[154:155], v[140:141] op_sel_hi:[1,0,1]
	s_and_b64 vcc, exec, s[44:45]
	v_pk_fma_f32 v[66:67], v[58:59], v[154:155], v[138:139] op_sel_hi:[1,0,1]
	v_cvt_pk_bf16_f32 v73, v68, v69
	flat_store_dwordx4 v[74:75], v[70:73] offset:256 sc1
	s_cbranch_vccnz .LBB0_274
	v_mul_f32_e32 v0, 0xbfb8aa3b, v62
	v_exp_f32_e32 v0, v0
	v_mul_f32_e32 v58, 0xbfb8aa3b, v66
	v_exp_f32_e32 v58, v58
	v_mul_f32_e32 v59, 0xbfb8aa3b, v67
	v_add_f32_e32 v0, 1.0, v0
	v_rcp_f32_e32 v62, v0
	v_mul_f32_e32 v0, 0xbfb8aa3b, v63
	v_exp_f32_e32 v0, v0
	v_exp_f32_e32 v59, v59
	v_add_f32_e32 v58, 1.0, v58
	v_rcp_f32_e32 v66, v58
	v_add_f32_e32 v0, 1.0, v0
	v_mul_f32_e32 v58, 0xbfb8aa3b, v64
	v_rcp_f32_e32 v63, v0
	v_add_f32_e32 v0, 1.0, v59
	v_exp_f32_e32 v58, v58
	v_mul_f32_e32 v59, 0xbfb8aa3b, v60
	v_exp_f32_e32 v59, v59
	v_rcp_f32_e32 v67, v0
	v_add_f32_e32 v0, 1.0, v58
	v_mul_f32_e32 v58, 0xbfb8aa3b, v65
	v_rcp_f32_e32 v64, v0
	v_add_f32_e32 v0, 1.0, v59
	v_exp_f32_e32 v58, v58
	v_mul_f32_e32 v59, 0xbfb8aa3b, v61
	v_exp_f32_e32 v59, v59
	v_rcp_f32_e32 v60, v0
	v_add_f32_e32 v0, 1.0, v58
	v_rcp_f32_e32 v65, v0
	v_add_f32_e32 v0, 1.0, v59
	v_rcp_f32_e32 v61, v0
.LBB0_274:
	v_mov_b32_e32 v155, v154
	v_mad_i64_i32 v[58:59], s[24:25], s12, v156, 0
	v_cvt_pk_bf16_f32 v62, v62, v63
	v_cvt_pk_bf16_f32 v63, v64, v65
	v_cvt_pk_bf16_f32 v64, v66, v67
	v_cvt_pk_bf16_f32 v65, v60, v61
	v_mov_b32_e32 v60, v154
	v_mov_b32_e32 v61, v154
	v_lshl_add_u64 v[58:59], v[58:59], 1, v[122:123]
	v_pk_fma_f32 v[56:57], v[56:57], v[60:61], v[136:137]
	v_pk_fma_f32 v[54:55], v[54:55], v[154:155], v[134:135]
	v_pk_fma_f32 v[52:53], v[52:53], v[60:61], v[132:133]
	s_and_b64 vcc, exec, s[44:45]
	v_pk_fma_f32 v[50:51], v[50:51], v[154:155], v[130:131]
	flat_store_dwordx4 v[58:59], v[62:65] sc1
	s_cbranch_vccnz .LBB0_276
	v_mul_f32_e32 v0, 0xbfb8aa3b, v54
	v_exp_f32_e32 v0, v0
	v_mul_f32_e32 v51, 0xbfb8aa3b, v51
	v_exp_f32_e32 v51, v51
	v_mul_f32_e32 v50, 0xbfb8aa3b, v50
	v_add_f32_e32 v0, 1.0, v0
	v_rcp_f32_e32 v54, v0
	v_mul_f32_e32 v0, 0xbfb8aa3b, v55
	v_exp_f32_e32 v0, v0
	v_exp_f32_e32 v50, v50
	v_add_f32_e32 v0, 1.0, v0
	v_rcp_f32_e32 v55, v0
	v_add_f32_e32 v0, 1.0, v51
	v_mul_f32_e32 v51, 0xbfb8aa3b, v56
	v_exp_f32_e32 v56, v51
	v_mul_f32_e32 v51, 0xbfb8aa3b, v52
	v_exp_f32_e32 v52, v51
	v_rcp_f32_e32 v51, v0
	v_add_f32_e32 v0, 1.0, v56
	v_rcp_f32_e32 v56, v0
	v_add_f32_e32 v0, 1.0, v52
	v_mul_f32_e32 v52, 0xbfb8aa3b, v57
	v_exp_f32_e32 v57, v52
	v_mul_f32_e32 v52, 0xbfb8aa3b, v53
	v_exp_f32_e32 v53, v52
	v_rcp_f32_e32 v52, v0
	v_add_f32_e32 v0, 1.0, v57
	v_add_f32_e32 v50, 1.0, v50
	v_rcp_f32_e32 v57, v0
	v_add_f32_e32 v0, 1.0, v53
	v_rcp_f32_e32 v50, v50
	v_rcp_f32_e32 v53, v0
.LBB0_276:
	v_cvt_pk_bf16_f32 v54, v54, v55
	v_cvt_pk_bf16_f32 v55, v56, v57
	v_cvt_pk_bf16_f32 v56, v50, v51
	v_pk_fma_f32 v[48:49], v[48:49], v[152:153], v[144:145] op_sel_hi:[1,0,1]
	v_pk_fma_f32 v[46:47], v[46:47], v[152:153], v[142:143] op_sel_hi:[1,0,1]
	v_pk_fma_f32 v[44:45], v[44:45], v[152:153], v[140:141] op_sel_hi:[1,0,1]
	s_and_b64 vcc, exec, s[44:45]
	v_pk_fma_f32 v[50:51], v[42:43], v[152:153], v[138:139] op_sel_hi:[1,0,1]
	v_cvt_pk_bf16_f32 v57, v52, v53
	flat_store_dwordx4 v[58:59], v[54:57] offset:256 sc1
	s_cbranch_vccnz .LBB0_278
	v_mul_f32_e32 v0, 0xbfb8aa3b, v46
	v_exp_f32_e32 v0, v0
	v_mul_f32_e32 v42, 0xbfb8aa3b, v50
	v_exp_f32_e32 v42, v42
	v_mul_f32_e32 v43, 0xbfb8aa3b, v51
	v_add_f32_e32 v0, 1.0, v0
	v_rcp_f32_e32 v46, v0
	v_mul_f32_e32 v0, 0xbfb8aa3b, v47
	v_exp_f32_e32 v0, v0
	v_exp_f32_e32 v43, v43
	v_add_f32_e32 v42, 1.0, v42
	v_rcp_f32_e32 v50, v42
	v_add_f32_e32 v0, 1.0, v0
	v_mul_f32_e32 v42, 0xbfb8aa3b, v48
	v_rcp_f32_e32 v47, v0
	v_add_f32_e32 v0, 1.0, v43
	v_exp_f32_e32 v42, v42
	v_mul_f32_e32 v43, 0xbfb8aa3b, v44
	v_exp_f32_e32 v43, v43
	v_rcp_f32_e32 v51, v0
	v_add_f32_e32 v0, 1.0, v42
	v_mul_f32_e32 v42, 0xbfb8aa3b, v49
	v_rcp_f32_e32 v48, v0
	v_add_f32_e32 v0, 1.0, v43
	v_exp_f32_e32 v42, v42
	v_mul_f32_e32 v43, 0xbfb8aa3b, v45
	v_exp_f32_e32 v43, v43
	v_rcp_f32_e32 v44, v0
	v_add_f32_e32 v0, 1.0, v42
	v_rcp_f32_e32 v49, v0
	v_add_f32_e32 v0, 1.0, v43
	v_rcp_f32_e32 v45, v0
.LBB0_278:
	v_add_u32_e32 v0, 0x90, v146
	v_mov_b32_e32 v153, v152
	v_mad_i64_i32 v[42:43], s[24:25], s12, v0, 0
	v_cvt_pk_bf16_f32 v46, v46, v47
	v_cvt_pk_bf16_f32 v47, v48, v49
	v_cvt_pk_bf16_f32 v48, v50, v51
	v_cvt_pk_bf16_f32 v49, v44, v45
	v_mov_b32_e32 v44, v152
	v_mov_b32_e32 v45, v152
	v_lshl_add_u64 v[42:43], v[42:43], 1, v[122:123]
	v_pk_fma_f32 v[40:41], v[40:41], v[44:45], v[136:137]
	v_pk_fma_f32 v[38:39], v[38:39], v[152:153], v[134:135]
	v_pk_fma_f32 v[36:37], v[36:37], v[44:45], v[132:133]
	s_and_b64 vcc, exec, s[44:45]
	v_pk_fma_f32 v[34:35], v[34:35], v[152:153], v[130:131]
	flat_store_dwordx4 v[42:43], v[46:49] sc1
	s_cbranch_vccnz .LBB0_280
	v_mul_f32_e32 v0, 0xbfb8aa3b, v38
	v_exp_f32_e32 v0, v0
	v_mul_f32_e32 v35, 0xbfb8aa3b, v35
	v_exp_f32_e32 v35, v35
	v_mul_f32_e32 v34, 0xbfb8aa3b, v34
	v_add_f32_e32 v0, 1.0, v0
	v_rcp_f32_e32 v38, v0
	v_mul_f32_e32 v0, 0xbfb8aa3b, v39
	v_exp_f32_e32 v0, v0
	v_exp_f32_e32 v34, v34
	v_add_f32_e32 v0, 1.0, v0
	v_rcp_f32_e32 v39, v0
	v_add_f32_e32 v0, 1.0, v35
	v_mul_f32_e32 v35, 0xbfb8aa3b, v40
	v_exp_f32_e32 v40, v35
	v_mul_f32_e32 v35, 0xbfb8aa3b, v36
	v_exp_f32_e32 v36, v35
	v_rcp_f32_e32 v35, v0
	v_add_f32_e32 v0, 1.0, v40
	v_rcp_f32_e32 v40, v0
	v_add_f32_e32 v0, 1.0, v36
	v_mul_f32_e32 v36, 0xbfb8aa3b, v41
	v_exp_f32_e32 v41, v36
	v_mul_f32_e32 v36, 0xbfb8aa3b, v37
	v_exp_f32_e32 v37, v36
	v_rcp_f32_e32 v36, v0
	v_add_f32_e32 v0, 1.0, v41
	v_add_f32_e32 v34, 1.0, v34
	v_rcp_f32_e32 v41, v0
	v_add_f32_e32 v0, 1.0, v37
	v_rcp_f32_e32 v34, v34
	v_rcp_f32_e32 v37, v0
; __device__ __forceinline__ unsigned cvt_pk_bf16(float lo, float hi) { unsigned r; asm volatile("v_cvt_pk_bf16_f32 %0, %1, %2" : "=v"(r) : "v"(lo), "v"(hi)); return r; }
; __device__ __forceinline__ float fast_sigmoid(float x) { return __builtin_amdgcn_rcpf(1.0f + __builtin_amdgcn_exp2f(-1.4426950408889634f * x)); }
;     __device__ __forceinline__ void operator()(const f32x4 (&acc)[2][2][4][2], const Unit& u, int wr, int wc, int fr, int fq) const {
;     ...
; #pragma unroll
;         for (int ai = 0; ai < 2; ++ai)
; #pragma unroll
;             for (int m = 0; m < 4; ++m) { bf16_t* rowp = base + (size_t)(row0 + ai * HALF + m * 16) * ldc + col0;
;                 const float rs = rsq[ai][m];
; #pragma unroll
;                 for (int bj = 0; bj < 2; ++bj) { f32x4 v0 = acc[ai][bj][m][0] * rs + bv[bj][0], v1 = acc[ai][bj][m][1] * rs + bv[bj][1];
;                     if (isg) {
; #pragma unroll
;                         for (int e = 0; e < 4; ++e) { v0[e] = fast_sigmoid(v0[e]); v1[e] = fast_sigmoid(v1[e]); } }
;                     u32x4 w; w.x = cvt_pk_bf16(v0[0], v0[1]); w.y = cvt_pk_bf16(v0[2], v0[3]); w.z = cvt_pk_bf16(v1[0], v1[1]); w.w = cvt_pk_bf16(v1[2], v1[3]);
;                     *(u32x4*)(rowp + bj * HALF) = w; } }
.LBB0_280:
	v_cvt_pk_bf16_f32 v38, v38, v39
	v_cvt_pk_bf16_f32 v39, v40, v41
	v_cvt_pk_bf16_f32 v40, v34, v35
	v_pk_fma_f32 v[32:33], v[32:33], v[150:151], v[144:145] op_sel_hi:[1,0,1]
	v_pk_fma_f32 v[30:31], v[30:31], v[150:151], v[142:143] op_sel_hi:[1,0,1]
	v_pk_fma_f32 v[28:29], v[28:29], v[150:151], v[140:141] op_sel_hi:[1,0,1]
	s_and_b64 vcc, exec, s[44:45]
	v_pk_fma_f32 v[34:35], v[26:27], v[150:151], v[138:139] op_sel_hi:[1,0,1]
	v_cvt_pk_bf16_f32 v41, v36, v37
	flat_store_dwordx4 v[42:43], v[38:41] offset:256 sc1
	s_cbranch_vccnz .LBB0_282
	v_mul_f32_e32 v0, 0xbfb8aa3b, v30
	v_exp_f32_e32 v0, v0
	v_mul_f32_e32 v26, 0xbfb8aa3b, v34
	v_exp_f32_e32 v26, v26
	v_mul_f32_e32 v27, 0xbfb8aa3b, v35
	v_add_f32_e32 v0, 1.0, v0
	v_rcp_f32_e32 v30, v0
	v_mul_f32_e32 v0, 0xbfb8aa3b, v31
	v_exp_f32_e32 v0, v0
	v_exp_f32_e32 v27, v27
	v_add_f32_e32 v26, 1.0, v26
	v_rcp_f32_e32 v34, v26
	v_add_f32_e32 v0, 1.0, v0
	v_mul_f32_e32 v26, 0xbfb8aa3b, v32
	v_rcp_f32_e32 v31, v0
	v_add_f32_e32 v0, 1.0, v27
	v_exp_f32_e32 v26, v26
	v_mul_f32_e32 v27, 0xbfb8aa3b, v28
	v_exp_f32_e32 v27, v27
	v_rcp_f32_e32 v35, v0
	v_add_f32_e32 v0, 1.0, v26
	v_mul_f32_e32 v26, 0xbfb8aa3b, v33
	v_rcp_f32_e32 v32, v0
	v_add_f32_e32 v0, 1.0, v27
	v_exp_f32_e32 v26, v26
	v_mul_f32_e32 v27, 0xbfb8aa3b, v29
	v_exp_f32_e32 v27, v27
	v_rcp_f32_e32 v28, v0
	v_add_f32_e32 v0, 1.0, v26
	v_rcp_f32_e32 v33, v0
	v_add_f32_e32 v0, 1.0, v27
	v_rcp_f32_e32 v29, v0
.LBB0_282:
	v_add_u32_e32 v0, 0xa0, v146
	v_mov_b32_e32 v151, v150
	v_mad_i64_i32 v[26:27], s[24:25], s12, v0, 0
	v_cvt_pk_bf16_f32 v30, v30, v31
	v_cvt_pk_bf16_f32 v31, v32, v33
	v_cvt_pk_bf16_f32 v32, v34, v35
	v_cvt_pk_bf16_f32 v33, v28, v29
	v_mov_b32_e32 v28, v150
	v_mov_b32_e32 v29, v150
	v_lshl_add_u64 v[26:27], v[26:27], 1, v[122:123]
	v_pk_fma_f32 v[24:25], v[24:25], v[28:29], v[136:137]
	v_pk_fma_f32 v[22:23], v[22:23], v[150:151], v[134:135]
	v_pk_fma_f32 v[20:21], v[20:21], v[28:29], v[132:133]
	s_and_b64 vcc, exec, s[44:45]
	v_pk_fma_f32 v[18:19], v[18:19], v[150:151], v[130:131]
	flat_store_dwordx4 v[26:27], v[30:33] sc1
	s_cbranch_vccnz .LBB0_284
	v_mul_f32_e32 v0, 0xbfb8aa3b, v22
	v_exp_f32_e32 v0, v0
	v_mul_f32_e32 v19, 0xbfb8aa3b, v19
	v_exp_f32_e32 v19, v19
	v_mul_f32_e32 v18, 0xbfb8aa3b, v18
	v_add_f32_e32 v0, 1.0, v0
	v_rcp_f32_e32 v22, v0
	v_mul_f32_e32 v0, 0xbfb8aa3b, v23
	v_exp_f32_e32 v0, v0
	v_exp_f32_e32 v18, v18
	v_add_f32_e32 v0, 1.0, v0
	v_rcp_f32_e32 v23, v0
	v_add_f32_e32 v0, 1.0, v19
	v_mul_f32_e32 v19, 0xbfb8aa3b, v24
	v_exp_f32_e32 v24, v19
	v_mul_f32_e32 v19, 0xbfb8aa3b, v20
	v_exp_f32_e32 v20, v19
	v_rcp_f32_e32 v19, v0
	v_add_f32_e32 v0, 1.0, v24
	v_rcp_f32_e32 v24, v0
	v_add_f32_e32 v0, 1.0, v20
	v_mul_f32_e32 v20, 0xbfb8aa3b, v25
	v_exp_f32_e32 v25, v20
	v_mul_f32_e32 v20, 0xbfb8aa3b, v21
	v_exp_f32_e32 v21, v20
	v_rcp_f32_e32 v20, v0
	v_add_f32_e32 v0, 1.0, v25
	v_add_f32_e32 v18, 1.0, v18
	v_rcp_f32_e32 v25, v0
	v_add_f32_e32 v0, 1.0, v21
	v_rcp_f32_e32 v18, v18
	v_rcp_f32_e32 v21, v0
.LBB0_284:
	v_cvt_pk_bf16_f32 v22, v22, v23
	v_cvt_pk_bf16_f32 v23, v24, v25
	v_cvt_pk_bf16_f32 v24, v18, v19
	v_pk_fma_f32 v[16:17], v[16:17], v[148:149], v[144:145] op_sel_hi:[1,0,1]
	v_pk_fma_f32 v[14:15], v[14:15], v[148:149], v[142:143] op_sel_hi:[1,0,1]
	v_pk_fma_f32 v[12:13], v[12:13], v[148:149], v[140:141] op_sel_hi:[1,0,1]
	s_and_b64 vcc, exec, s[44:45]
	v_pk_fma_f32 v[18:19], v[10:11], v[148:149], v[138:139] op_sel_hi:[1,0,1]
	v_cvt_pk_bf16_f32 v25, v20, v21
	flat_store_dwordx4 v[26:27], v[22:25] offset:256 sc1
	s_cbranch_vccnz .LBB0_286
	v_mul_f32_e32 v0, 0xbfb8aa3b, v14
	v_exp_f32_e32 v0, v0
	v_mul_f32_e32 v10, 0xbfb8aa3b, v18
	v_exp_f32_e32 v10, v10
	v_mul_f32_e32 v11, 0xbfb8aa3b, v19
	v_add_f32_e32 v0, 1.0, v0
	v_rcp_f32_e32 v14, v0
	v_mul_f32_e32 v0, 0xbfb8aa3b, v15
	v_exp_f32_e32 v0, v0
	v_exp_f32_e32 v11, v11
	v_add_f32_e32 v10, 1.0, v10
	v_rcp_f32_e32 v18, v10
	v_add_f32_e32 v0, 1.0, v0
	v_mul_f32_e32 v10, 0xbfb8aa3b, v16
	v_rcp_f32_e32 v15, v0
	v_add_f32_e32 v0, 1.0, v11
	v_exp_f32_e32 v10, v10
	v_mul_f32_e32 v11, 0xbfb8aa3b, v12
	v_exp_f32_e32 v11, v11
	v_rcp_f32_e32 v19, v0
	v_add_f32_e32 v0, 1.0, v10
	v_mul_f32_e32 v10, 0xbfb8aa3b, v17
	v_rcp_f32_e32 v16, v0
	v_add_f32_e32 v0, 1.0, v11
	v_exp_f32_e32 v10, v10
	v_mul_f32_e32 v11, 0xbfb8aa3b, v13
	v_exp_f32_e32 v11, v11
	v_rcp_f32_e32 v12, v0
	v_add_f32_e32 v0, 1.0, v10
	v_rcp_f32_e32 v17, v0
	v_add_f32_e32 v0, 1.0, v11
	v_rcp_f32_e32 v13, v0
.LBB0_286:
	v_add_u32_e32 v0, 0xb0, v146
	v_mov_b32_e32 v149, v148
	v_mad_i64_i32 v[10:11], s[12:13], s12, v0, 0
	v_cvt_pk_bf16_f32 v14, v14, v15
	v_cvt_pk_bf16_f32 v15, v16, v17
	v_cvt_pk_bf16_f32 v16, v18, v19
	v_cvt_pk_bf16_f32 v17, v12, v13
	v_mov_b32_e32 v12, v148
	v_mov_b32_e32 v13, v148
	v_lshl_add_u64 v[10:11], v[10:11], 1, v[122:123]
	v_pk_fma_f32 v[8:9], v[8:9], v[12:13], v[136:137]
	v_pk_fma_f32 v[6:7], v[6:7], v[148:149], v[134:135]
	v_pk_fma_f32 v[4:5], v[4:5], v[12:13], v[132:133]
	s_and_b64 vcc, exec, s[44:45]
	v_pk_fma_f32 v[2:3], v[2:3], v[148:149], v[130:131]
	flat_store_dwordx4 v[10:11], v[14:17] sc1
	s_cbranch_vccnz .LBB0_288
	v_mul_f32_e32 v0, 0xbfb8aa3b, v6
	v_exp_f32_e32 v0, v0
	v_mul_f32_e32 v3, 0xbfb8aa3b, v3
	v_exp_f32_e32 v3, v3
	v_mul_f32_e32 v2, 0xbfb8aa3b, v2
	v_add_f32_e32 v0, 1.0, v0
	v_rcp_f32_e32 v6, v0
	v_mul_f32_e32 v0, 0xbfb8aa3b, v7
	v_exp_f32_e32 v0, v0
	v_exp_f32_e32 v2, v2
	v_add_f32_e32 v0, 1.0, v0
	v_rcp_f32_e32 v7, v0
	v_add_f32_e32 v0, 1.0, v3
	v_mul_f32_e32 v3, 0xbfb8aa3b, v8
	v_exp_f32_e32 v8, v3
	v_mul_f32_e32 v3, 0xbfb8aa3b, v4
	v_exp_f32_e32 v4, v3
	v_rcp_f32_e32 v3, v0
	v_add_f32_e32 v0, 1.0, v8
	v_rcp_f32_e32 v8, v0
	v_add_f32_e32 v0, 1.0, v4
	v_mul_f32_e32 v4, 0xbfb8aa3b, v9
	v_exp_f32_e32 v9, v4
	v_mul_f32_e32 v4, 0xbfb8aa3b, v5
	v_exp_f32_e32 v5, v4
	v_rcp_f32_e32 v4, v0
	v_add_f32_e32 v0, 1.0, v9
	v_add_f32_e32 v2, 1.0, v2
	v_rcp_f32_e32 v9, v0
	v_add_f32_e32 v0, 1.0, v5
	v_rcp_f32_e32 v2, v2
	v_rcp_f32_e32 v5, v0
.LBB0_288:
	v_cvt_pk_bf16_f32 v6, v6, v7
	v_cvt_pk_bf16_f32 v7, v8, v9
	v_cvt_pk_bf16_f32 v8, v2, v3
	v_cvt_pk_bf16_f32 v9, v4, v5
	flat_store_dwordx4 v[10:11], v[6:9] offset:256 sc1
	s_and_b64 vcc, exec, s[42:43]
	s_mov_b64 s[12:13], -1
	s_cbranch_vccnz .LBB0_124
